# as v12 plus EpiLru per-unit lambda parameter loads issued together
# baseline (speedup 1.0000x reference)
;     __device__ __forceinline__ void operator()(const f32x4 (&acc)[2][2][4][2], const Unit& u, int wr, int wc, int fr, int fq, const float (&rs)[2][4]) const {
;     ...
;         for (int j = 0; j < 8; ++j) { ba[j] = b_a[dir * 512 + cbase + j]; bx[j] = b_x[dir * 512 + cbase + j];
;             const float e = __expf(-lam[dir * 512 + cbase + j]);
;             sp[j] = 8.0f * LOG2E * (e < 0.02f ? e * (1.0f - e * (0.5f - e * (0.33333333f - 0.25f * e))) : __logf(1.0f + e)); }
.LBB0_1057:
	s_lshl_b32 s0, s2, 7
	s_and_b32 s1, s0, 0x180
	v_mov_b32_e32 v143, v150
	v_mov_b32_e32 v130, v151
	s_or_b32 s1, s1, s40
	s_and_b32 s64, s0, 0xfffffe00
	v_lshl_add_u32 v142, v130, 3, s1
	v_add_u32_e32 v130, s64, v142
	v_ashrrev_i32_e32 v131, 31, v130
	v_readlane_b32 s0, v255, 24
	v_lshlrev_b64 v[130:131], 2, v[130:131]
	v_readlane_b32 s1, v255, 25
	s_nop 1
	v_lshl_add_u64 v[144:145], s[0:1], 0, v[130:131]
	global_load_dword v200, v[144:145], off
	global_load_dword v201, v[144:145], off offset:4
	global_load_dword v202, v[144:145], off offset:8
	global_load_dword v203, v[144:145], off offset:12
	global_load_dword v204, v[144:145], off offset:16
	global_load_dword v205, v[144:145], off offset:20
	global_load_dword v206, v[144:145], off offset:24
	global_load_dword v207, v[144:145], off offset:28
	v_readlane_b32 s0, v255, 20
	v_readlane_b32 s1, v255, 21
	s_nop 1
	v_lshl_add_u64 v[146:147], s[0:1], 0, v[130:131]
	v_readlane_b32 s0, v255, 22
	v_readlane_b32 s1, v255, 23
	global_load_dword v173, v[146:147], off
	s_nop 0
	v_lshl_add_u64 v[148:149], s[0:1], 0, v[130:131]
	global_load_dword v170, v[148:149], off
	s_waitcnt vmcnt(2)
	v_mul_f32_e32 v130, 0xbfb8aa3b, v200
	v_exp_f32_e32 v154, v130
	s_nop 0
	v_cmp_ngt_f32_e32 vcc, s14, v154
	s_and_saveexec_b64 s[0:1], vcc
	s_xor_b64 s[68:69], exec, s[0:1]
	s_cbranch_execz .LBB0_1059
	v_add_f32_e32 v130, 1.0, v154
	v_cmp_gt_f32_e32 vcc, s10, v130
	s_nop 1
	v_cndmask_b32_e64 v131, 0, 32, vcc
	v_ldexp_f32 v130, v130, v131
	v_log_f32_e32 v130, v130
	s_nop 0
	v_mul_f32_e32 v131, 0x3f317217, v130
	v_fma_f32 v131, v130, s15, -v131
	v_fmac_f32_e32 v131, 0x3377d1cf, v130
	v_fmac_f32_e32 v131, 0x3f317217, v130
	v_cmp_lt_f32_e64 s[2:3], |v130|, s16
	s_nop 1
	v_cndmask_b32_e64 v130, v130, v131, s[2:3]
	v_cndmask_b32_e32 v131, 0, v175, vcc
	v_sub_f32_e32 v183, v130, v131
.LBB0_1059:
	s_andn2_saveexec_b64 s[2:3], s[68:69]
	v_fmamk_f32 v130, v154, 0xbe800000, v252
	v_fma_f32 v130, -v154, v130, 0.5
	v_fma_f32 v130, -v154, v130, 1.0
	v_mul_f32_e32 v183, v154, v130
	s_or_b64 exec, exec, s[2:3]
	global_load_dword v168, v[146:147], off offset:4
	global_load_dword v166, v[148:149], off offset:4
	v_mul_f32_e32 v130, 0xbfb8aa3b, v201
	v_exp_f32_e32 v154, v130
	s_nop 0
	v_cmp_ngt_f32_e32 vcc, s14, v154
	s_and_saveexec_b64 s[0:1], vcc
	s_xor_b64 s[68:69], exec, s[0:1]
	s_cbranch_execz .LBB0_1063
	v_add_f32_e32 v130, 1.0, v154
	v_cmp_gt_f32_e32 vcc, s10, v130
	s_nop 1
	v_cndmask_b32_e64 v131, 0, 32, vcc
	v_ldexp_f32 v130, v130, v131
	v_log_f32_e32 v130, v130
	s_nop 0
	v_mul_f32_e32 v131, 0x3f317217, v130
	v_fma_f32 v131, v130, s15, -v131
	v_fmac_f32_e32 v131, 0x3377d1cf, v130
	v_fmac_f32_e32 v131, 0x3f317217, v130
	v_cmp_lt_f32_e64 s[2:3], |v130|, s16
	s_nop 1
	v_cndmask_b32_e64 v130, v130, v131, s[2:3]
	v_cndmask_b32_e32 v131, 0, v175, vcc
	v_sub_f32_e32 v182, v130, v131
.LBB0_1063:
	s_andn2_saveexec_b64 s[2:3], s[68:69]
	v_fmamk_f32 v130, v154, 0xbe800000, v252
	v_fma_f32 v130, -v154, v130, 0.5
	v_fma_f32 v130, -v154, v130, 1.0
	v_mul_f32_e32 v182, v154, v130
	s_or_b64 exec, exec, s[2:3]
	global_load_dword v164, v[146:147], off offset:8
	global_load_dword v163, v[148:149], off offset:8
	v_mul_f32_e32 v130, 0xbfb8aa3b, v202
	v_exp_f32_e32 v154, v130
	s_nop 0
	v_cmp_ngt_f32_e32 vcc, s14, v154
	s_and_saveexec_b64 s[0:1], vcc
	s_xor_b64 s[68:69], exec, s[0:1]
	s_cbranch_execz .LBB0_1067
	v_add_f32_e32 v130, 1.0, v154
	v_cmp_gt_f32_e32 vcc, s10, v130
	s_nop 1
	v_cndmask_b32_e64 v131, 0, 32, vcc
	v_ldexp_f32 v130, v130, v131
	v_log_f32_e32 v130, v130
	s_nop 0
	v_mul_f32_e32 v131, 0x3f317217, v130
	v_fma_f32 v131, v130, s15, -v131
	v_fmac_f32_e32 v131, 0x3377d1cf, v130
	v_fmac_f32_e32 v131, 0x3f317217, v130
	v_cmp_lt_f32_e64 s[2:3], |v130|, s16
	s_nop 1
	v_cndmask_b32_e64 v130, v130, v131, s[2:3]
	v_cndmask_b32_e32 v131, 0, v175, vcc
	v_sub_f32_e32 v181, v130, v131
.LBB0_1067:
	s_andn2_saveexec_b64 s[2:3], s[68:69]
	v_fmamk_f32 v130, v154, 0xbe800000, v252
	v_fma_f32 v130, -v154, v130, 0.5
	v_fma_f32 v130, -v154, v130, 1.0
	v_mul_f32_e32 v181, v154, v130
	s_or_b64 exec, exec, s[2:3]
	global_load_dword v162, v[146:147], off offset:12
	global_load_dword v161, v[148:149], off offset:12
	v_mul_f32_e32 v130, 0xbfb8aa3b, v203
	v_exp_f32_e32 v154, v130
	s_nop 0
	v_cmp_ngt_f32_e32 vcc, s14, v154
	s_and_saveexec_b64 s[0:1], vcc
	s_xor_b64 s[68:69], exec, s[0:1]
	s_cbranch_execz .LBB0_1071
	v_add_f32_e32 v130, 1.0, v154
	v_cmp_gt_f32_e32 vcc, s10, v130
	s_nop 1
	v_cndmask_b32_e64 v131, 0, 32, vcc
	v_ldexp_f32 v130, v130, v131
	v_log_f32_e32 v130, v130
	s_nop 0
	v_mul_f32_e32 v131, 0x3f317217, v130
	v_fma_f32 v131, v130, s15, -v131
	v_fmac_f32_e32 v131, 0x3377d1cf, v130
	v_fmac_f32_e32 v131, 0x3f317217, v130
	v_cmp_lt_f32_e64 s[2:3], |v130|, s16
	s_nop 1
	v_cndmask_b32_e64 v130, v130, v131, s[2:3]
	v_cndmask_b32_e32 v131, 0, v175, vcc
	v_sub_f32_e32 v172, v130, v131
;     __device__ __forceinline__ void operator()(const f32x4 (&acc)[2][2][4][2], const Unit& u, int wr, int wc, int fr, int fq, const float (&rs)[2][4]) const {
;     ...
;         for (int j = 0; j < 8; ++j) { ba[j] = b_a[dir * 512 + cbase + j]; bx[j] = b_x[dir * 512 + cbase + j];
;             const float e = __expf(-lam[dir * 512 + cbase + j]);
;             sp[j] = 8.0f * LOG2E * (e < 0.02f ? e * (1.0f - e * (0.5f - e * (0.33333333f - 0.25f * e))) : __logf(1.0f + e)); }
.LBB0_1071:
	s_andn2_saveexec_b64 s[2:3], s[68:69]
	v_fmamk_f32 v130, v154, 0xbe800000, v252
	v_fma_f32 v130, -v154, v130, 0.5
	v_fma_f32 v130, -v154, v130, 1.0
	v_mul_f32_e32 v172, v154, v130
	s_or_b64 exec, exec, s[2:3]
	global_load_dword v159, v[146:147], off offset:16
	global_load_dword v158, v[148:149], off offset:16
	v_mul_f32_e32 v130, 0xbfb8aa3b, v204
	v_exp_f32_e32 v154, v130
	s_nop 0
	v_cmp_ngt_f32_e32 vcc, s14, v154
	s_and_saveexec_b64 s[0:1], vcc
	s_xor_b64 s[68:69], exec, s[0:1]
	s_cbranch_execz .LBB0_1075
	v_add_f32_e32 v130, 1.0, v154
	v_cmp_gt_f32_e32 vcc, s10, v130
	s_nop 1
	v_cndmask_b32_e64 v131, 0, 32, vcc
	v_ldexp_f32 v130, v130, v131
	v_log_f32_e32 v130, v130
	s_nop 0
	v_mul_f32_e32 v131, 0x3f317217, v130
	v_fma_f32 v131, v130, s15, -v131
	v_fmac_f32_e32 v131, 0x3377d1cf, v130
	v_fmac_f32_e32 v131, 0x3f317217, v130
	v_cmp_lt_f32_e64 s[2:3], |v130|, s16
	s_nop 1
	v_cndmask_b32_e64 v130, v130, v131, s[2:3]
	v_cndmask_b32_e32 v131, 0, v175, vcc
	v_sub_f32_e32 v165, v130, v131
.LBB0_1075:
	s_andn2_saveexec_b64 s[2:3], s[68:69]
	v_fmamk_f32 v130, v154, 0xbe800000, v252
	v_fma_f32 v130, -v154, v130, 0.5
	v_fma_f32 v130, -v154, v130, 1.0
	v_mul_f32_e32 v165, v154, v130
	s_or_b64 exec, exec, s[2:3]
	global_load_dword v157, v[146:147], off offset:20
	global_load_dword v156, v[148:149], off offset:20
	v_mul_f32_e32 v130, 0xbfb8aa3b, v205
	v_exp_f32_e32 v154, v130
	s_nop 0
	v_cmp_ngt_f32_e32 vcc, s14, v154
	s_and_saveexec_b64 s[0:1], vcc
	s_xor_b64 s[68:69], exec, s[0:1]
	s_cbranch_execz .LBB0_1079
	v_add_f32_e32 v130, 1.0, v154
	v_cmp_gt_f32_e32 vcc, s10, v130
	s_nop 1
	v_cndmask_b32_e64 v131, 0, 32, vcc
	v_ldexp_f32 v130, v130, v131
	v_log_f32_e32 v130, v130
	s_nop 0
	v_mul_f32_e32 v131, 0x3f317217, v130
	v_fma_f32 v131, v130, s15, -v131
	v_fmac_f32_e32 v131, 0x3377d1cf, v130
	v_fmac_f32_e32 v131, 0x3f317217, v130
	v_cmp_lt_f32_e64 s[2:3], |v130|, s16
	s_nop 1
	v_cndmask_b32_e64 v130, v130, v131, s[2:3]
	v_cndmask_b32_e32 v131, 0, v175, vcc
	v_sub_f32_e32 v160, v130, v131
.LBB0_1079:
	s_andn2_saveexec_b64 s[2:3], s[68:69]
	v_fmamk_f32 v130, v154, 0xbe800000, v252
	v_fma_f32 v130, -v154, v130, 0.5
	v_fma_f32 v130, -v154, v130, 1.0
	v_mul_f32_e32 v160, v154, v130
	s_or_b64 exec, exec, s[2:3]
	global_load_dword v155, v[146:147], off offset:24
	global_load_dword v154, v[148:149], off offset:24
	v_mul_f32_e32 v130, 0xbfb8aa3b, v206
	v_exp_f32_e32 v185, v130
	s_nop 0
	v_cmp_ngt_f32_e32 vcc, s14, v185
	s_and_saveexec_b64 s[0:1], vcc
	s_xor_b64 s[68:69], exec, s[0:1]
	s_cbranch_execz .LBB0_1083
	v_add_f32_e32 v130, 1.0, v185
	v_cmp_gt_f32_e32 vcc, s10, v130
	s_nop 1
	v_cndmask_b32_e64 v131, 0, 32, vcc
	v_ldexp_f32 v130, v130, v131
	v_log_f32_e32 v130, v130
	s_nop 0
	v_mul_f32_e32 v131, 0x3f317217, v130
	v_fma_f32 v131, v130, s15, -v131
	v_fmac_f32_e32 v131, 0x3377d1cf, v130
	v_fmac_f32_e32 v131, 0x3f317217, v130
	v_cmp_lt_f32_e64 s[2:3], |v130|, s16
	s_nop 1
	v_cndmask_b32_e64 v130, v130, v131, s[2:3]
	v_cndmask_b32_e32 v131, 0, v175, vcc
	v_sub_f32_e32 v184, v130, v131
.LBB0_1083:
	s_andn2_saveexec_b64 s[2:3], s[68:69]
	v_fmamk_f32 v130, v185, 0xbe800000, v252
	v_fma_f32 v130, -v185, v130, 0.5
	v_fma_f32 v130, -v185, v130, 1.0
	v_mul_f32_e32 v184, v185, v130
	s_or_b64 exec, exec, s[2:3]
	s_nop 0
	global_load_dword v147, v[146:147], off offset:28
	s_nop 0
	global_load_dword v146, v[148:149], off offset:28
	s_waitcnt vmcnt(0)
	v_mul_f32_e32 v130, 0xbfb8aa3b, v207
	v_exp_f32_e32 v145, v130
	s_nop 0
	v_cmp_ngt_f32_e32 vcc, s14, v145
	s_and_saveexec_b64 s[0:1], vcc
	s_xor_b64 s[68:69], exec, s[0:1]
	s_cbranch_execz .LBB0_1087
	v_add_f32_e32 v130, 1.0, v145
	v_cmp_gt_f32_e32 vcc, s10, v130
	s_nop 1
	v_cndmask_b32_e64 v131, 0, 32, vcc
	v_ldexp_f32 v130, v130, v131
	v_log_f32_e32 v130, v130
	s_nop 0
	v_mul_f32_e32 v131, 0x3f317217, v130
	v_fma_f32 v131, v130, s15, -v131
	v_fmac_f32_e32 v131, 0x3377d1cf, v130
	v_fmac_f32_e32 v131, 0x3f317217, v130
	v_cmp_lt_f32_e64 s[2:3], |v130|, s16
	s_nop 1
	v_cndmask_b32_e64 v130, v130, v131, s[2:3]
	v_cndmask_b32_e32 v131, 0, v175, vcc
	v_sub_f32_e32 v144, v130, v131
